# v25 + in-projection K-loop: the mid-run s_setprio 0 / s_setprio 1 pair inside each 32-MFMA phase removed (one priority window per phase)
# speedup vs baseline: 1.0067x; 1.0067x over previous
; #define PG8_STAGE(bufoff, gbase, voff) do { _Pragma("unroll") for (int _i = 0; _i < 2; ++_i) \
;         __builtin_amdgcn_global_load_lds((const unsigned*)((const char*)(gbase) + (voff)[_i]), (PG8_LAS unsigned*)(lds + (bufoff) + ldsw + _i * 8192), 16, 0, 0); } while (0)
; #define PG8_LDA(dst, b, h) do { _Pragma("unroll") for (int m = 0; m < 4; ++m) _Pragma("unroll") for (int k = 0; k < 2; ++k) dst[m][k] = *(const PG8_LAS bf16x8*)(lds + PG8_SA(b, h) + aoff + m * 2048 + k * 1024); } while (0)
; #define PG8_LDB(dst, b, h) do { _Pragma("unroll") for (int n = 0; n < 2; ++n) _Pragma("unroll") for (int k = 0; k < 2; ++k) dst[n][k] = *(const PG8_LAS bf16x8*)(lds + PG8_SB(b, h) + boff + n * 2048 + k * 1024); } while (0)
; #define PG8_MMA(ai, bj, At, Bt) do { __builtin_amdgcn_s_setprio(1); _Pragma("unroll") for (int m = 0; m < 4; ++m) _Pragma("unroll") for (int n = 0; n < 2; ++n) _Pragma("unroll") for (int k = 0; k < 2; ++k) \
;         acc[ai][bj][m][n] = __builtin_amdgcn_mfma_f32_16x16x32_bf16(Bt[n][k], At[m][k], acc[ai][bj][m][n], 0, 0, 0); __builtin_amdgcn_s_setprio(0); } while (0)
; #define PG8_WAIT_V(n) asm volatile("s_waitcnt vmcnt(" #n ")" ::: "memory")
; #define PG8_WAIT_L(n) asm volatile("s_waitcnt lgkmcnt(" #n ")" ::: "memory")
; template <class Epi, class Sched, bool ALIGN_EPI = false, bool SP2 = false>
; __device__ __forceinline__ void gemm_phase(PG8_LAS unsigned char* lds, const Gemm g, const Sched& S, const Epi& E, const int tid) {
;     ...
;             const bool last = (t == nt - 2);
;             const char* a1 = cA + (size_t)(t + 1) * kstep;
;             const char* a2 = last ? nA : cA + (size_t)(t + 2) * kstep; const char* b2 = last ? nB : cB + (size_t)(t + 2) * kstep;
;             const char* a3 = a2 + kstep; const char* b3 = b2 + kstep;
;             if (last && has_next) S.a_ready(nxt);
;             if constexpr (SP2) {
;             PG8_LDB(B0, 0, 0); PG8_LDB(B1, 0, 1); PG8_SCHED; PG8_LDA(At, 0, 0); PG8_STAGE(PG8_SA(1, 1), a1 + hstepA, voffA);
;             PG8_WAIT_V(8); PG8_WAIT_L(0); PG8_BAR; PG8_MMA(0, 0, At, B0); PG8_MMA(0, 1, At, B1); PG8_BAR; PG8_SCHED;
;             PG8_LDA(At, 0, 1); PG8_STAGE(PG8_SB(0, 0), b2, voffB); PG8_STAGE(PG8_SB(0, 1), b2 + hstepB, voffB); PG8_STAGE(PG8_SA(0, 0), a2, voffA);
;             PG8_WAIT_V(8); PG8_WAIT_L(0); PG8_BAR; PG8_MMA(1, 0, At, B0); PG8_MMA(1, 1, At, B1); PG8_BAR; PG8_SCHED;
.LBB0_175:
	s_add_u32 s22, s6, 0xfff80080
	s_addc_u32 s23, s7, -1
	s_add_i32 s60, 0, 0x10000
	s_cmp_eq_u32 s59, 28
	s_cselect_b32 s25, s17, s23
	s_cselect_b32 s24, s27, s22
	s_cselect_b32 s23, s15, s43
	s_cselect_b32 s22, s28, s29
	s_add_i32 s62, 0, 0x14000
	v_add_u32_e32 v140, s60, v225
	v_add_u32_e32 v156, s62, v225
	ds_read_b128 v[128:131], v140
	ds_read_b128 v[132:135], v140 offset:1024
	ds_read_b128 v[136:139], v140 offset:2048
	ds_read_b128 v[140:143], v140 offset:3072
	ds_read_b128 v[144:147], v156
	ds_read_b128 v[148:151], v156 offset:1024
	ds_read_b128 v[152:155], v156 offset:2048
	ds_read_b128 v[156:159], v156 offset:3072
	v_lshl_add_u64 v[202:203], s[6:7], 0, v[186:187]
	s_add_i32 m0, s46, 0xc000
	ds_read_b128 v[160:163], v226
	ds_read_b128 v[164:167], v226 offset:1024
	ds_read_b128 v[168:171], v226 offset:2048
	ds_read_b128 v[172:175], v226 offset:3072
	ds_read_b128 v[188:191], v226 offset:4096
	ds_read_b128 v[194:197], v226 offset:5120
	ds_read_b128 v[198:201], v226 offset:6144
	ds_read_b128 v[218:221], v226 offset:7168
	global_load_lds_dwordx4 v[202:203], off
	v_lshl_add_u64 v[202:203], s[6:7], 0, v[184:185]
	s_add_i32 m0, s46, 0xe000
	s_nop 0
	global_load_lds_dwordx4 v[202:203], off
	s_waitcnt vmcnt(8)
	s_waitcnt lgkmcnt(0)
	s_barrier
	s_setprio 1
	s_waitcnt lgkmcnt(0)
	v_mfma_f32_16x16x32_bf16 v[120:123], v[128:131], v[160:163], v[120:123]
	v_mfma_f32_16x16x32_bf16 v[112:115], v[136:139], v[160:163], v[112:115]
	v_mfma_f32_16x16x32_bf16 v[76:79], v[128:131], v[168:171], v[76:79]
	v_mfma_f32_16x16x32_bf16 v[60:63], v[136:139], v[168:171], v[60:63]
	v_mfma_f32_16x16x32_bf16 v[52:55], v[128:131], v[188:191], v[52:55]
	v_mfma_f32_16x16x32_bf16 v[36:39], v[136:139], v[188:191], v[36:39]
	v_mfma_f32_16x16x32_bf16 v[32:35], v[128:131], v[198:201], v[32:35]
	v_mfma_f32_16x16x32_bf16 v[24:27], v[136:139], v[198:201], v[24:27]
	v_mfma_f32_16x16x32_bf16 v[120:123], v[132:135], v[164:167], v[120:123]
	v_mfma_f32_16x16x32_bf16 v[112:115], v[140:143], v[164:167], v[112:115]
	v_mfma_f32_16x16x32_bf16 v[76:79], v[132:135], v[172:175], v[76:79]
	v_mfma_f32_16x16x32_bf16 v[60:63], v[140:143], v[172:175], v[60:63]
	v_mfma_f32_16x16x32_bf16 v[52:55], v[132:135], v[194:197], v[52:55]
	v_mfma_f32_16x16x32_bf16 v[36:39], v[140:143], v[194:197], v[36:39]
	v_mfma_f32_16x16x32_bf16 v[32:35], v[132:135], v[218:221], v[32:35]
	v_mfma_f32_16x16x32_bf16 v[24:27], v[140:143], v[218:221], v[24:27]
	v_mfma_f32_16x16x32_bf16 v[124:127], v[144:147], v[160:163], v[124:127]
	v_mfma_f32_16x16x32_bf16 v[116:119], v[152:155], v[160:163], v[116:119]
	v_mfma_f32_16x16x32_bf16 v[84:87], v[144:147], v[168:171], v[84:87]
	v_mfma_f32_16x16x32_bf16 v[68:71], v[152:155], v[168:171], v[68:71]
	v_mfma_f32_16x16x32_bf16 v[64:67], v[144:147], v[188:191], v[64:67]
	v_mfma_f32_16x16x32_bf16 v[48:51], v[152:155], v[188:191], v[48:51]
	v_mfma_f32_16x16x32_bf16 v[44:47], v[144:147], v[198:201], v[44:47]
	v_mfma_f32_16x16x32_bf16 v[28:31], v[152:155], v[198:201], v[28:31]
	v_mfma_f32_16x16x32_bf16 v[124:127], v[148:151], v[164:167], v[124:127]
	v_mfma_f32_16x16x32_bf16 v[116:119], v[156:159], v[164:167], v[116:119]
	v_mfma_f32_16x16x32_bf16 v[84:87], v[148:151], v[172:175], v[84:87]
	v_mfma_f32_16x16x32_bf16 v[68:71], v[156:159], v[172:175], v[68:71]
	v_mfma_f32_16x16x32_bf16 v[64:67], v[148:151], v[194:197], v[64:67]
	v_mfma_f32_16x16x32_bf16 v[48:51], v[156:159], v[194:197], v[48:51]
	v_mfma_f32_16x16x32_bf16 v[44:47], v[148:151], v[218:221], v[44:47]
	v_mfma_f32_16x16x32_bf16 v[28:31], v[156:159], v[218:221], v[28:31]
	s_setprio 0
	s_barrier
	s_add_i32 s60, s60, s37
	v_lshl_add_u64 v[202:203], s[22:23], 0, v[180:181]
	s_mov_b32 m0, s60
	ds_read_b128 v[160:163], v226 offset:16384
	ds_read_b128 v[164:167], v226 offset:17408
	ds_read_b128 v[168:171], v226 offset:18432
	ds_read_b128 v[172:175], v226 offset:19456
	ds_read_b128 v[188:191], v226 offset:20480
	ds_read_b128 v[194:197], v226 offset:21504
	ds_read_b128 v[198:201], v226 offset:22528
	ds_read_b128 v[218:221], v226 offset:23552
	global_load_lds_dwordx4 v[202:203], off
	s_add_i32 m0, s60, 0x2000
	s_add_u32 s60, s22, 0x80000
	v_lshl_add_u64 v[206:207], s[22:23], 0, v[176:177]
	s_addc_u32 s61, s23, 0
	s_add_i32 s62, s62, s37
	global_load_lds_dwordx4 v[206:207], off
	v_lshl_add_u64 v[208:209], s[60:61], 0, v[180:181]
	s_mov_b32 m0, s62
	v_lshl_add_u64 v[214:215], s[24:25], 0, v[178:179]
	global_load_lds_dwordx4 v[208:209], off
	v_lshl_add_u64 v[208:209], s[60:61], 0, v[176:177]
	s_add_i32 m0, s62, 0x2000
	s_nop 0
	global_load_lds_dwordx4 v[208:209], off
	v_lshl_add_u64 v[208:209], s[24:25], 0, v[182:183]
	s_mov_b32 m0, s46
	s_nop 0
	global_load_lds_dwordx4 v[208:209], off
	s_mov_b32 m0, s47
	s_nop 0
	global_load_lds_dwordx4 v[214:215], off
	s_waitcnt vmcnt(8)
	s_waitcnt lgkmcnt(0)
	s_barrier
; #define PG8_STAGE(bufoff, gbase, voff) do { _Pragma("unroll") for (int _i = 0; _i < 2; ++_i) \
;         __builtin_amdgcn_global_load_lds((const unsigned*)((const char*)(gbase) + (voff)[_i]), (PG8_LAS unsigned*)(lds + (bufoff) + ldsw + _i * 8192), 16, 0, 0); } while (0)
; #define PG8_LDA(dst, b, h) do { _Pragma("unroll") for (int m = 0; m < 4; ++m) _Pragma("unroll") for (int k = 0; k < 2; ++k) dst[m][k] = *(const PG8_LAS bf16x8*)(lds + PG8_SA(b, h) + aoff + m * 2048 + k * 1024); } while (0)
; #define PG8_LDB(dst, b, h) do { _Pragma("unroll") for (int n = 0; n < 2; ++n) _Pragma("unroll") for (int k = 0; k < 2; ++k) dst[n][k] = *(const PG8_LAS bf16x8*)(lds + PG8_SB(b, h) + boff + n * 2048 + k * 1024); } while (0)
; #define PG8_MMA(ai, bj, At, Bt) do { __builtin_amdgcn_s_setprio(1); _Pragma("unroll") for (int m = 0; m < 4; ++m) _Pragma("unroll") for (int n = 0; n < 2; ++n) _Pragma("unroll") for (int k = 0; k < 2; ++k) \
;         acc[ai][bj][m][n] = __builtin_amdgcn_mfma_f32_16x16x32_bf16(Bt[n][k], At[m][k], acc[ai][bj][m][n], 0, 0, 0); __builtin_amdgcn_s_setprio(0); } while (0)
; #define PG8_WAIT_V(n) asm volatile("s_waitcnt vmcnt(" #n ")" ::: "memory")
; #define PG8_WAIT_L(n) asm volatile("s_waitcnt lgkmcnt(" #n ")" ::: "memory")
; #define PG8_BAR __builtin_amdgcn_s_barrier()
; #define PG8_SCHED __builtin_amdgcn_sched_barrier(0)
; template <class Epi, class Sched, bool ALIGN_EPI = false, bool SP2 = false>
; __device__ __forceinline__ void gemm_phase(PG8_LAS unsigned char* lds, const Gemm g, const Sched& S, const Epi& E, const int tid) {
;     ...
;             PG8_WAIT_V(8); PG8_WAIT_L(0); PG8_BAR; PG8_MMA(1, 0, At, B0); PG8_MMA(1, 1, At, B1); PG8_BAR; PG8_SCHED;
;             PG8_LDB(B0, 1, 0); PG8_LDB(B1, 1, 1); PG8_SCHED; PG8_LDA(At, 1, 0); PG8_STAGE(PG8_SA(0, 1), a2 + hstepA, voffA);
;             PG8_WAIT_V(8); PG8_WAIT_L(0); PG8_BAR; PG8_MMA(0, 0, At, B0); PG8_MMA(0, 1, At, B1); PG8_BAR; PG8_SCHED;
	s_setprio 1
	s_waitcnt lgkmcnt(0)
	v_mfma_f32_16x16x32_bf16 v[96:99], v[128:131], v[160:163], v[96:99]
	v_mfma_f32_16x16x32_bf16 v[100:103], v[136:139], v[160:163], v[100:103]
	v_mfma_f32_16x16x32_bf16 v[72:75], v[128:131], v[168:171], v[72:75]
	v_mfma_f32_16x16x32_bf16 v[80:83], v[136:139], v[168:171], v[80:83]
	v_mfma_f32_16x16x32_bf16 v[16:19], v[128:131], v[188:191], v[16:19]
	v_mfma_f32_16x16x32_bf16 v[20:23], v[136:139], v[188:191], v[20:23]
	v_mfma_f32_16x16x32_bf16 v[0:3], v[128:131], v[198:201], v[0:3]
	v_mfma_f32_16x16x32_bf16 v[4:7], v[136:139], v[198:201], v[4:7]
	v_mfma_f32_16x16x32_bf16 v[96:99], v[132:135], v[164:167], v[96:99]
	v_mfma_f32_16x16x32_bf16 v[100:103], v[140:143], v[164:167], v[100:103]
	v_mfma_f32_16x16x32_bf16 v[72:75], v[132:135], v[172:175], v[72:75]
	v_mfma_f32_16x16x32_bf16 v[80:83], v[140:143], v[172:175], v[80:83]
	v_mfma_f32_16x16x32_bf16 v[16:19], v[132:135], v[194:197], v[16:19]
	v_mfma_f32_16x16x32_bf16 v[20:23], v[140:143], v[194:197], v[20:23]
	v_mfma_f32_16x16x32_bf16 v[0:3], v[132:135], v[218:221], v[0:3]
	v_mfma_f32_16x16x32_bf16 v[4:7], v[140:143], v[218:221], v[4:7]
	v_mfma_f32_16x16x32_bf16 v[108:111], v[144:147], v[160:163], v[108:111]
	v_mfma_f32_16x16x32_bf16 v[104:107], v[152:155], v[160:163], v[104:107]
	v_mfma_f32_16x16x32_bf16 v[92:95], v[144:147], v[168:171], v[92:95]
	v_mfma_f32_16x16x32_bf16 v[88:91], v[152:155], v[168:171], v[88:91]
	v_mfma_f32_16x16x32_bf16 v[56:59], v[144:147], v[188:191], v[56:59]
	v_mfma_f32_16x16x32_bf16 v[40:43], v[152:155], v[188:191], v[40:43]
	v_mfma_f32_16x16x32_bf16 v[8:11], v[144:147], v[198:201], v[8:11]
	v_mfma_f32_16x16x32_bf16 v[12:15], v[152:155], v[198:201], v[12:15]
	v_mfma_f32_16x16x32_bf16 v[108:111], v[148:151], v[164:167], v[108:111]
	v_mfma_f32_16x16x32_bf16 v[104:107], v[156:159], v[164:167], v[104:107]
	v_mfma_f32_16x16x32_bf16 v[92:95], v[148:151], v[172:175], v[92:95]
	v_mfma_f32_16x16x32_bf16 v[88:91], v[156:159], v[172:175], v[88:91]
	v_mfma_f32_16x16x32_bf16 v[56:59], v[148:151], v[194:197], v[56:59]
	v_mfma_f32_16x16x32_bf16 v[40:43], v[156:159], v[194:197], v[40:43]
	v_mfma_f32_16x16x32_bf16 v[8:11], v[148:151], v[218:221], v[8:11]
	v_mfma_f32_16x16x32_bf16 v[12:15], v[156:159], v[218:221], v[12:15]
	s_setprio 0
	s_barrier
	s_add_i32 s60, 0, 0x18000
	s_add_i32 s61, 0, 0x1c000
	v_add_u32_e32 v140, s60, v225
	v_add_u32_e32 v156, s61, v225
	ds_read_b128 v[128:131], v140
	ds_read_b128 v[132:135], v140 offset:1024
	ds_read_b128 v[136:139], v140 offset:2048
	ds_read_b128 v[140:143], v140 offset:3072
	ds_read_b128 v[144:147], v156
	ds_read_b128 v[148:151], v156 offset:1024
	ds_read_b128 v[152:155], v156 offset:2048
	ds_read_b128 v[156:159], v156 offset:3072
	s_add_u32 s24, s24, 0x80000
	s_addc_u32 s25, s25, 0
	s_mov_b32 m0, s48
	v_lshl_add_u64 v[216:217], s[24:25], 0, v[182:183]
	ds_read_b128 v[160:163], v226 offset:32768
	ds_read_b128 v[164:167], v226 offset:33792
	ds_read_b128 v[168:171], v226 offset:34816
	ds_read_b128 v[172:175], v226 offset:35840
	ds_read_b128 v[188:191], v226 offset:36864
	ds_read_b128 v[194:197], v226 offset:37888
	ds_read_b128 v[198:201], v226 offset:38912
	ds_read_b128 v[218:221], v226 offset:39936
	global_load_lds_dwordx4 v[216:217], off
	v_lshl_add_u64 v[216:217], s[24:25], 0, v[178:179]
	s_mov_b32 m0, s49
	s_nop 0
	global_load_lds_dwordx4 v[216:217], off
	s_waitcnt vmcnt(8)
	s_waitcnt lgkmcnt(0)
	s_barrier
	s_setprio 1
	s_waitcnt lgkmcnt(0)
	v_mfma_f32_16x16x32_bf16 v[120:123], v[128:131], v[160:163], v[120:123]
	v_mfma_f32_16x16x32_bf16 v[112:115], v[136:139], v[160:163], v[112:115]
	v_mfma_f32_16x16x32_bf16 v[76:79], v[128:131], v[168:171], v[76:79]
	v_mfma_f32_16x16x32_bf16 v[60:63], v[136:139], v[168:171], v[60:63]
	v_mfma_f32_16x16x32_bf16 v[52:55], v[128:131], v[188:191], v[52:55]
	v_mfma_f32_16x16x32_bf16 v[36:39], v[136:139], v[188:191], v[36:39]
	v_mfma_f32_16x16x32_bf16 v[32:35], v[128:131], v[198:201], v[32:35]
	v_mfma_f32_16x16x32_bf16 v[24:27], v[136:139], v[198:201], v[24:27]
	v_mfma_f32_16x16x32_bf16 v[120:123], v[132:135], v[164:167], v[120:123]
	v_mfma_f32_16x16x32_bf16 v[112:115], v[140:143], v[164:167], v[112:115]
	v_mfma_f32_16x16x32_bf16 v[76:79], v[132:135], v[172:175], v[76:79]
	v_mfma_f32_16x16x32_bf16 v[60:63], v[140:143], v[172:175], v[60:63]
	v_mfma_f32_16x16x32_bf16 v[52:55], v[132:135], v[194:197], v[52:55]
	v_mfma_f32_16x16x32_bf16 v[36:39], v[140:143], v[194:197], v[36:39]
	v_mfma_f32_16x16x32_bf16 v[32:35], v[132:135], v[218:221], v[32:35]
	v_mfma_f32_16x16x32_bf16 v[24:27], v[140:143], v[218:221], v[24:27]
	v_mfma_f32_16x16x32_bf16 v[124:127], v[144:147], v[160:163], v[124:127]
	v_mfma_f32_16x16x32_bf16 v[116:119], v[152:155], v[160:163], v[116:119]
	v_mfma_f32_16x16x32_bf16 v[84:87], v[144:147], v[168:171], v[84:87]
	v_mfma_f32_16x16x32_bf16 v[68:71], v[152:155], v[168:171], v[68:71]
	v_mfma_f32_16x16x32_bf16 v[64:67], v[144:147], v[188:191], v[64:67]
	v_mfma_f32_16x16x32_bf16 v[48:51], v[152:155], v[188:191], v[48:51]
	v_mfma_f32_16x16x32_bf16 v[44:47], v[144:147], v[198:201], v[44:47]
	v_mfma_f32_16x16x32_bf16 v[28:31], v[152:155], v[198:201], v[28:31]
	v_mfma_f32_16x16x32_bf16 v[124:127], v[148:151], v[164:167], v[124:127]
	v_mfma_f32_16x16x32_bf16 v[116:119], v[156:159], v[164:167], v[116:119]
	v_mfma_f32_16x16x32_bf16 v[84:87], v[148:151], v[172:175], v[84:87]
	v_mfma_f32_16x16x32_bf16 v[68:71], v[156:159], v[172:175], v[68:71]
	v_mfma_f32_16x16x32_bf16 v[64:67], v[148:151], v[194:197], v[64:67]
	v_mfma_f32_16x16x32_bf16 v[48:51], v[156:159], v[194:197], v[48:51]
	v_mfma_f32_16x16x32_bf16 v[44:47], v[148:151], v[218:221], v[44:47]
	v_mfma_f32_16x16x32_bf16 v[28:31], v[156:159], v[218:221], v[28:31]
	s_setprio 0
	s_barrier
; #define PG8_STAGE(bufoff, gbase, voff) do { _Pragma("unroll") for (int _i = 0; _i < 2; ++_i) \
;         __builtin_amdgcn_global_load_lds((const unsigned*)((const char*)(gbase) + (voff)[_i]), (PG8_LAS unsigned*)(lds + (bufoff) + ldsw + _i * 8192), 16, 0, 0); } while (0)
; #define PG8_LDA(dst, b, h) do { _Pragma("unroll") for (int m = 0; m < 4; ++m) _Pragma("unroll") for (int k = 0; k < 2; ++k) dst[m][k] = *(const PG8_LAS bf16x8*)(lds + PG8_SA(b, h) + aoff + m * 2048 + k * 1024); } while (0)
; #define PG8_MMA(ai, bj, At, Bt) do { __builtin_amdgcn_s_setprio(1); _Pragma("unroll") for (int m = 0; m < 4; ++m) _Pragma("unroll") for (int n = 0; n < 2; ++n) _Pragma("unroll") for (int k = 0; k < 2; ++k) \
;         acc[ai][bj][m][n] = __builtin_amdgcn_mfma_f32_16x16x32_bf16(Bt[n][k], At[m][k], acc[ai][bj][m][n], 0, 0, 0); __builtin_amdgcn_s_setprio(0); } while (0)
; #define PG8_WAIT_V(n) asm volatile("s_waitcnt vmcnt(" #n ")" ::: "memory")
; #define PG8_WAIT_L(n) asm volatile("s_waitcnt lgkmcnt(" #n ")" ::: "memory")
; #define PG8_BAR __builtin_amdgcn_s_barrier()
; #define PG8_SCHED __builtin_amdgcn_sched_barrier(0)
; template <class Epi, class Sched, bool ALIGN_EPI = false, bool SP2 = false>
; __device__ __forceinline__ void gemm_phase(PG8_LAS unsigned char* lds, const Gemm g, const Sched& S, const Epi& E, const int tid) {
;     ...
;             PG8_LDA(At, 1, 1); PG8_STAGE(PG8_SB(1, 0), b3, voffB); PG8_STAGE(PG8_SB(1, 1), b3 + hstepB, voffB); PG8_STAGE(PG8_SA(1, 0), a3, voffA);
;             PG8_WAIT_V(8); PG8_WAIT_L(0); PG8_BAR; PG8_MMA(1, 0, At, B0); PG8_MMA(1, 1, At, B1); PG8_BAR; PG8_SCHED;
	s_add_i32 s24, s60, s37
	v_lshl_add_u64 v[202:203], v[202:203], 0, s[82:83]
	s_mov_b32 m0, s24
	ds_read_b128 v[160:163], v226 offset:49152
	ds_read_b128 v[164:167], v226 offset:50176
	ds_read_b128 v[168:171], v226 offset:51200
	ds_read_b128 v[172:175], v226 offset:52224
	ds_read_b128 v[188:191], v226 offset:53248
	ds_read_b128 v[194:197], v226 offset:54272
	ds_read_b128 v[198:201], v226 offset:55296
	ds_read_b128 v[218:221], v226 offset:56320
	global_load_lds_dwordx4 v[202:203], off
	s_add_i32 m0, s24, 0x2000
	s_add_u32 s22, s22, 0x80080
	v_lshl_add_u64 v[202:203], v[206:207], 0, s[82:83]
	s_addc_u32 s23, s23, 0
	s_add_i32 s24, s61, s37
	global_load_lds_dwordx4 v[202:203], off
	v_lshl_add_u64 v[202:203], s[22:23], 0, v[180:181]
	s_mov_b32 m0, s24
	s_nop 0
	global_load_lds_dwordx4 v[202:203], off
	v_lshl_add_u64 v[202:203], s[22:23], 0, v[176:177]
	s_add_i32 m0, s24, 0x2000
	s_nop 0
	global_load_lds_dwordx4 v[202:203], off
	v_lshl_add_u64 v[202:203], v[208:209], 0, s[82:83]
	s_mov_b32 m0, s54
	s_nop 0
	global_load_lds_dwordx4 v[202:203], off
	v_lshl_add_u64 v[202:203], v[214:215], 0, s[82:83]
	s_mov_b32 m0, s55
	s_nop 0
	global_load_lds_dwordx4 v[202:203], off
	s_waitcnt vmcnt(8)
	s_waitcnt lgkmcnt(0)
	s_barrier
	s_setprio 1
	s_waitcnt lgkmcnt(0)
	v_mfma_f32_16x16x32_bf16 v[96:99], v[128:131], v[160:163], v[96:99]
	v_mfma_f32_16x16x32_bf16 v[100:103], v[136:139], v[160:163], v[100:103]
	v_mfma_f32_16x16x32_bf16 v[72:75], v[128:131], v[168:171], v[72:75]
	v_mfma_f32_16x16x32_bf16 v[80:83], v[136:139], v[168:171], v[80:83]
	v_mfma_f32_16x16x32_bf16 v[16:19], v[128:131], v[188:191], v[16:19]
	v_mfma_f32_16x16x32_bf16 v[20:23], v[136:139], v[188:191], v[20:23]
	v_mfma_f32_16x16x32_bf16 v[0:3], v[128:131], v[198:201], v[0:3]
	v_mfma_f32_16x16x32_bf16 v[4:7], v[136:139], v[198:201], v[4:7]
	v_mfma_f32_16x16x32_bf16 v[96:99], v[132:135], v[164:167], v[96:99]
	v_mfma_f32_16x16x32_bf16 v[100:103], v[140:143], v[164:167], v[100:103]
	v_mfma_f32_16x16x32_bf16 v[72:75], v[132:135], v[172:175], v[72:75]
	v_mfma_f32_16x16x32_bf16 v[80:83], v[140:143], v[172:175], v[80:83]
	v_mfma_f32_16x16x32_bf16 v[16:19], v[132:135], v[194:197], v[16:19]
	v_mfma_f32_16x16x32_bf16 v[20:23], v[140:143], v[194:197], v[20:23]
	v_mfma_f32_16x16x32_bf16 v[0:3], v[132:135], v[218:221], v[0:3]
	v_mfma_f32_16x16x32_bf16 v[4:7], v[140:143], v[218:221], v[4:7]
	v_mfma_f32_16x16x32_bf16 v[108:111], v[144:147], v[160:163], v[108:111]
	v_mfma_f32_16x16x32_bf16 v[104:107], v[152:155], v[160:163], v[104:107]
	v_mfma_f32_16x16x32_bf16 v[92:95], v[144:147], v[168:171], v[92:95]
	v_mfma_f32_16x16x32_bf16 v[88:91], v[152:155], v[168:171], v[88:91]
	v_mfma_f32_16x16x32_bf16 v[56:59], v[144:147], v[188:191], v[56:59]
	v_mfma_f32_16x16x32_bf16 v[40:43], v[152:155], v[188:191], v[40:43]
	v_mfma_f32_16x16x32_bf16 v[8:11], v[144:147], v[198:201], v[8:11]
	v_mfma_f32_16x16x32_bf16 v[12:15], v[152:155], v[198:201], v[12:15]
	v_mfma_f32_16x16x32_bf16 v[108:111], v[148:151], v[164:167], v[108:111]
	v_mfma_f32_16x16x32_bf16 v[104:107], v[156:159], v[164:167], v[104:107]
	v_mfma_f32_16x16x32_bf16 v[92:95], v[148:151], v[172:175], v[92:95]
	v_mfma_f32_16x16x32_bf16 v[88:91], v[156:159], v[172:175], v[88:91]
	v_mfma_f32_16x16x32_bf16 v[56:59], v[148:151], v[194:197], v[56:59]
	v_mfma_f32_16x16x32_bf16 v[40:43], v[156:159], v[194:197], v[40:43]
	v_mfma_f32_16x16x32_bf16 v[8:11], v[148:151], v[218:221], v[8:11]
	v_mfma_f32_16x16x32_bf16 v[12:15], v[156:159], v[218:221], v[12:15]
	s_setprio 0
	s_barrier
	s_add_i32 s59, s59, 2
	s_add_u32 s29, s29, 0x100
	s_addc_u32 s43, s43, 0
	s_add_u32 s6, s6, 0x100
	s_addc_u32 s7, s7, 0
	s_cmp_gt_u32 s59, 29
	s_cbranch_scc0 .LBB0_175
	s_and_b64 vcc, exec, s[12:13]
	s_cbranch_vccz .LBB0_178
	s_barrier
